# phase 12: the 16 workgroups owning a K/V GEMM tile skip the row-norm loop, others take their rows; plus gdn transition pass rewrite
# baseline (speedup 1.0000x reference)
; #define UNPK8N(dst, u) do { dst[0] = bflo(u.x); dst[1] = bfhi(u.x); dst[2] = bflo(u.y); dst[3] = bfhi(u.y); dst[4] = bflo(u.z); dst[5] = bfhi(u.z); dst[6] = bflo(u.w); dst[7] = bfhi(u.w); } while (0)
; __device__ __forceinline__ void rownorm_bd(const bf16_t* hsrc, const bf16_t* dsrc, bf16_t* hdst, bf16_t* udst, int rows, int wg, int nwg) {
;     const int lane = threadIdx.x & 63, wid = threadIdx.x >> 6;
;     for (int row = wg * 8 + wid; row < rows; row += nwg * 8) {
;         const u32x4* ph = (const u32x4*)(hsrc + (size_t)row * D); const u32x4* pd = (const u32x4*)(dsrc + (size_t)row * D);
;         float v[4][8]; float ss = 0.f;
; #pragma unroll
;         for (int i = 0; i < 4; ++i) { const u32x4 a = ph[lane + 64 * i], b = pd[lane + 64 * i]; float x[8], y[8]; UNPK8N(x, a); UNPK8N(y, b);
; #pragma unroll
;             for (int e = 0; e < 8; ++e) { v[i][e] = x[e] + y[e]; ss += v[i][e] * v[i][e]; } }
; __global__ void __launch_bounds__(512, 2) fwd_megakernel(Params P) {
;     ...
;     rownorm_bd(hb, hb2, hb, (bf16_t*)(ws + WS_HQ), T, wg, nwg);
;     run_gemm<2>(lds, (const bf16_t*)(ws + WS_MKVN), D, (const bf16_t*)(ws + WS_MK), NMEM, D, D, ws + WS_KM, D, nullptr, 0, 0.f, 0);
;     run_gemm<2>(lds, (const bf16_t*)(ws + WS_MV), D, (const bf16_t*)(ws + WS_MKVN), D, NMEM, D, ws + WS_VT, NMEM, nullptr, 0, 0.f, 8);
.LBB0_1073:
	s_or_b64 exec, exec, s[8:9]
	s_waitcnt lgkmcnt(0)
	s_barrier
	s_mov_b64 s[10:11], exec
	s_sub_i32 s100, s28, 8
	s_cmp_lt_u32 s2, 8
	s_cbranch_scc1 .LBB0_1076
	s_cmp_ge_u32 s2, s100
	s_cbranch_scc1 .LBB0_1076
	s_and_saveexec_b64 s[10:11], s[4:5]
	s_cbranch_execz .LBB0_1076
	v_mbcnt_hi_u32_b32 v2, -1, v1
	v_and_b32_e32 v3, 64, v2
	v_add_u32_e32 v3, 64, v3
	v_xor_b32_e32 v4, 32, v2
	v_cmp_lt_i32_e32 vcc, v4, v3
	v_subrev_u32_e32 v220, 64, v162
	v_ashrrev_i32_e32 v221, 31, v220
	v_lshlrev_b64 v[6:7], 12, v[220:221]
	s_sub_i32 s100, s42, 0x80
	s_ashr_i32 s101, s100, 31
	v_cndmask_b32_e32 v4, v2, v4, vcc
	v_lshlrev_b32_e32 v12, 2, v4
	v_xor_b32_e32 v4, 16, v2
	v_cmp_lt_i32_e32 vcc, v4, v3
	s_lshl_b64 s[12:13], s[100:101], 12
	s_mov_b64 s[14:15], 0
	v_cndmask_b32_e32 v4, v2, v4, vcc
	v_lshlrev_b32_e32 v13, 2, v4
	v_xor_b32_e32 v4, 8, v2
	v_cmp_lt_i32_e32 vcc, v4, v3
	v_mov_b32_e32 v18, 0x358637bd
	s_mov_b32 s41, 0x800000
	v_cndmask_b32_e32 v4, v2, v4, vcc
	v_lshlrev_b32_e32 v14, 2, v4
	v_xor_b32_e32 v4, 4, v2
	v_cmp_lt_i32_e32 vcc, v4, v3
	s_mov_b32 s43, 0xdc00000
	s_movk_i32 s44, 0x3fff
	v_cndmask_b32_e32 v4, v2, v4, vcc
	v_lshlrev_b32_e32 v15, 2, v4
	v_xor_b32_e32 v4, 2, v2
	v_cmp_lt_i32_e32 vcc, v4, v3
	v_mov_b32_e32 v19, v220
	s_nop 0
	v_cndmask_b32_e32 v4, v2, v4, vcc
	v_lshlrev_b32_e32 v16, 2, v4
	v_xor_b32_e32 v4, 1, v2
	v_cmp_lt_i32_e32 vcc, v4, v3
	v_mov_b32_e32 v3, 0
	s_nop 0
	v_cndmask_b32_e32 v2, v2, v4, vcc
	v_lshlrev_b32_e32 v17, 2, v2
	v_lshlrev_b32_e32 v2, 4, v160
	v_lshl_add_u64 v[4:5], s[26:27], 0, v[6:7]
	v_lshl_add_u64 v[6:7], s[24:25], 0, v[6:7]
.LBB0_1075:
	v_lshl_add_u64 v[10:11], v[4:5], 0, v[2:3]
	v_lshl_add_u64 v[8:9], v[6:7], 0, v[2:3]
	v_add_co_u32_e32 v48, vcc, 0x1ac00000, v10
	global_load_dwordx4 v[20:23], v[8:9], off
	global_load_dwordx4 v[24:27], v[8:9], off offset:1024
	global_load_dwordx4 v[28:31], v[8:9], off offset:2048
	v_addc_co_u32_e32 v49, vcc, 0, v11, vcc
	global_load_dwordx4 v[32:35], v[8:9], off offset:3072
	global_load_dwordx4 v[36:39], v[48:49], off
	global_load_dwordx4 v[40:43], v[48:49], off offset:1024
	global_load_dwordx4 v[44:47], v[48:49], off offset:2048
	s_nop 0
	global_load_dwordx4 v[48:51], v[48:49], off offset:3072
	v_add_co_u32_e64 v52, s[8:9], s43, v10
	v_add_u32_e32 v19, s100, v19
	s_nop 0
	v_addc_co_u32_e64 v53, s[8:9], 0, v11, s[8:9]
	v_cmp_lt_i32_e64 s[8:9], s44, v19
	v_lshl_add_u64 v[4:5], v[4:5], 0, s[12:13]
	v_lshl_add_u64 v[6:7], v[6:7], 0, s[12:13]
	s_or_b64 s[14:15], s[8:9], s[14:15]
	s_waitcnt vmcnt(7)
	v_lshlrev_b32_e32 v10, 16, v20
	v_and_b32_e32 v11, 0xffff0000, v20
	v_lshlrev_b32_e32 v20, 16, v21
	s_waitcnt vmcnt(3)
	v_lshlrev_b32_e32 v68, 16, v36
	v_and_b32_e32 v69, 0xffff0000, v36
	v_and_b32_e32 v21, 0xffff0000, v21
	v_lshlrev_b32_e32 v54, 16, v22
	v_and_b32_e32 v55, 0xffff0000, v22
	v_lshlrev_b32_e32 v22, 16, v23
	v_and_b32_e32 v23, 0xffff0000, v23
	v_lshlrev_b32_e32 v36, 16, v37
	v_and_b32_e32 v37, 0xffff0000, v37
	v_lshlrev_b32_e32 v70, 16, v38
	v_and_b32_e32 v71, 0xffff0000, v38
	v_lshlrev_b32_e32 v38, 16, v39
	v_and_b32_e32 v39, 0xffff0000, v39
	v_pk_add_f32 v[10:11], v[10:11], v[68:69]
	v_pk_add_f32 v[36:37], v[20:21], v[36:37]
	v_pk_add_f32 v[54:55], v[54:55], v[70:71]
	v_pk_add_f32 v[38:39], v[22:23], v[38:39]
	v_pk_mul_f32 v[68:69], v[10:11], v[10:11]
	v_pk_mul_f32 v[70:71], v[36:37], v[36:37]
	v_cvt_pk_bf16_f32 v20, v10, v11
	v_cvt_pk_bf16_f32 v21, v36, v37
	v_cvt_pk_bf16_f32 v22, v54, v55
	v_cvt_pk_bf16_f32 v23, v38, v39
	v_add_f32_e32 v68, v68, v69
	v_lshlrev_b32_e32 v56, 16, v24
	v_and_b32_e32 v57, 0xffff0000, v24
	s_waitcnt vmcnt(2)
	v_lshlrev_b32_e32 v72, 16, v40
	v_and_b32_e32 v73, 0xffff0000, v40
	global_store_dwordx4 v[8:9], v[20:23], off
	v_pk_add_f32 v[56:57], v[56:57], v[72:73]
	v_pk_mul_f32 v[72:73], v[54:55], v[54:55]
	v_add_f32_e32 v20, v70, v68
	v_add_f32_e32 v20, v71, v20
	v_lshlrev_b32_e32 v58, 16, v26
	v_and_b32_e32 v59, 0xffff0000, v26
	v_lshlrev_b32_e32 v74, 16, v42
	v_and_b32_e32 v75, 0xffff0000, v42
	v_add_f32_e32 v20, v72, v20
	v_pk_add_f32 v[58:59], v[58:59], v[74:75]
	v_pk_mul_f32 v[74:75], v[38:39], v[38:39]
	v_add_f32_e32 v20, v73, v20
	v_lshlrev_b32_e32 v60, 16, v28
	v_and_b32_e32 v61, 0xffff0000, v28
	s_waitcnt vmcnt(2)
	v_lshlrev_b32_e32 v76, 16, v44
	v_and_b32_e32 v77, 0xffff0000, v44
	v_add_f32_e32 v20, v74, v20
	v_lshlrev_b32_e32 v24, 16, v25
	v_and_b32_e32 v25, 0xffff0000, v25
	v_lshlrev_b32_e32 v40, 16, v41
	v_and_b32_e32 v41, 0xffff0000, v41
	v_pk_add_f32 v[60:61], v[60:61], v[76:77]
	v_pk_mul_f32 v[76:77], v[56:57], v[56:57]
	v_add_f32_e32 v20, v75, v20
	v_lshlrev_b32_e32 v62, 16, v30
	v_and_b32_e32 v63, 0xffff0000, v30
	v_lshlrev_b32_e32 v78, 16, v46
	v_and_b32_e32 v79, 0xffff0000, v46
	v_pk_add_f32 v[40:41], v[24:25], v[40:41]
	v_add_f32_e32 v20, v76, v20
	v_pk_add_f32 v[62:63], v[62:63], v[78:79]
	v_pk_mul_f32 v[78:79], v[40:41], v[40:41]
	v_add_f32_e32 v20, v77, v20
	v_lshlrev_b32_e32 v64, 16, v32
	v_and_b32_e32 v65, 0xffff0000, v32
	s_waitcnt vmcnt(1)
; __device__ __forceinline__ unsigned cvt_pk_bf16(float lo, float hi) { const bf16x2n v = __builtin_convertvector((f32x2){lo, hi}, bf16x2n); return __builtin_bit_cast(unsigned, v); }
; #define UNPK8N(dst, u) do { dst[0] = bflo(u.x); dst[1] = bfhi(u.x); dst[2] = bflo(u.y); dst[3] = bfhi(u.y); dst[4] = bflo(u.z); dst[5] = bfhi(u.z); dst[6] = bflo(u.w); dst[7] = bfhi(u.w); } while (0)
; __device__ __forceinline__ void rownorm_bd(const bf16_t* hsrc, const bf16_t* dsrc, bf16_t* hdst, bf16_t* udst, int rows, int wg, int nwg) {
;     ...
;         for (int i = 0; i < 4; ++i) { const u32x4 a = ph[lane + 64 * i], b = pd[lane + 64 * i]; float x[8], y[8]; UNPK8N(x, a); UNPK8N(y, b);
; #pragma unroll
;             for (int e = 0; e < 8; ++e) { v[i][e] = x[e] + y[e]; ss += v[i][e] * v[i][e]; } }
;         ss = wave_sum(ss);
;         const float rs = rsqrtf(ss * (1.f / D) + 1e-6f);
; #pragma unroll
;         for (int i = 0; i < 4; ++i) {
;             u32x4 w; w.x = cvt_pk_bf16(v[i][0], v[i][1]); w.y = cvt_pk_bf16(v[i][2], v[i][3]); w.z = cvt_pk_bf16(v[i][4], v[i][5]); w.w = cvt_pk_bf16(v[i][6], v[i][7]);
;             *(u32x4*)(hdst + (size_t)row * D + (lane + 64 * i) * 8) = w;
;             u32x4 z; z.x = cvt_pk_bf16(v[i][0] * rs, v[i][1] * rs); z.y = cvt_pk_bf16(v[i][2] * rs, v[i][3] * rs); z.z = cvt_pk_bf16(v[i][4] * rs, v[i][5] * rs); z.w = cvt_pk_bf16(v[i][6] * rs, v[i][7] * rs);
;             *(u32x4*)(udst + (size_t)row * D + (lane + 64 * i) * 8) = z;
;         }
	v_lshlrev_b32_e32 v80, 16, v48
	v_and_b32_e32 v81, 0xffff0000, v48
	v_add_f32_e32 v20, v78, v20
	v_lshlrev_b32_e32 v26, 16, v27
	v_and_b32_e32 v27, 0xffff0000, v27
	v_lshlrev_b32_e32 v42, 16, v43
	v_and_b32_e32 v43, 0xffff0000, v43
	v_pk_add_f32 v[64:65], v[64:65], v[80:81]
	v_pk_mul_f32 v[80:81], v[58:59], v[58:59]
	v_add_f32_e32 v20, v79, v20
	v_lshlrev_b32_e32 v66, 16, v34
	v_and_b32_e32 v67, 0xffff0000, v34
	v_lshlrev_b32_e32 v82, 16, v50
	v_and_b32_e32 v83, 0xffff0000, v50
	v_pk_add_f32 v[42:43], v[26:27], v[42:43]
	v_add_f32_e32 v20, v80, v20
	v_pk_add_f32 v[66:67], v[66:67], v[82:83]
	v_pk_mul_f32 v[82:83], v[42:43], v[42:43]
	v_add_f32_e32 v20, v81, v20
	v_add_f32_e32 v20, v82, v20
	v_lshlrev_b32_e32 v28, 16, v29
	v_and_b32_e32 v29, 0xffff0000, v29
	v_lshlrev_b32_e32 v44, 16, v45
	v_and_b32_e32 v45, 0xffff0000, v45
	v_pk_mul_f32 v[84:85], v[60:61], v[60:61]
	v_add_f32_e32 v20, v83, v20
	v_pk_add_f32 v[44:45], v[28:29], v[44:45]
	v_add_f32_e32 v20, v84, v20
	v_pk_mul_f32 v[86:87], v[44:45], v[44:45]
	v_add_f32_e32 v20, v85, v20
	v_add_f32_e32 v20, v86, v20
	v_lshlrev_b32_e32 v30, 16, v31
	v_and_b32_e32 v31, 0xffff0000, v31
	v_lshlrev_b32_e32 v46, 16, v47
	v_and_b32_e32 v47, 0xffff0000, v47
	v_pk_mul_f32 v[88:89], v[62:63], v[62:63]
	v_add_f32_e32 v20, v87, v20
	v_pk_add_f32 v[46:47], v[30:31], v[46:47]
	v_add_f32_e32 v20, v88, v20
	v_pk_mul_f32 v[90:91], v[46:47], v[46:47]
	v_add_f32_e32 v20, v89, v20
	v_add_f32_e32 v20, v90, v20
	v_lshlrev_b32_e32 v32, 16, v33
	v_and_b32_e32 v33, 0xffff0000, v33
	v_lshlrev_b32_e32 v48, 16, v49
	v_and_b32_e32 v49, 0xffff0000, v49
	v_pk_mul_f32 v[92:93], v[64:65], v[64:65]
	v_add_f32_e32 v20, v91, v20
	v_pk_add_f32 v[48:49], v[32:33], v[48:49]
	v_add_f32_e32 v20, v92, v20
	v_pk_mul_f32 v[94:95], v[48:49], v[48:49]
	v_add_f32_e32 v20, v93, v20
	v_add_f32_e32 v20, v94, v20
	v_lshlrev_b32_e32 v34, 16, v35
	v_and_b32_e32 v35, 0xffff0000, v35
	v_lshlrev_b32_e32 v50, 16, v51
	v_and_b32_e32 v51, 0xffff0000, v51
	v_pk_mul_f32 v[96:97], v[66:67], v[66:67]
	v_add_f32_e32 v20, v95, v20
	v_pk_add_f32 v[50:51], v[34:35], v[50:51]
	v_add_f32_e32 v20, v96, v20
	v_pk_mul_f32 v[98:99], v[50:51], v[50:51]
	v_add_f32_e32 v20, v97, v20
	v_add_f32_e32 v20, v98, v20
	v_add_f32_e32 v20, v99, v20
	ds_bpermute_b32 v21, v12, v20
	v_cvt_pk_bf16_f32 v24, v56, v57
	v_cvt_pk_bf16_f32 v25, v40, v41
	v_cvt_pk_bf16_f32 v26, v58, v59
	v_cvt_pk_bf16_f32 v27, v42, v43
	s_waitcnt lgkmcnt(0)
	v_add_f32_e32 v20, v20, v21
	ds_bpermute_b32 v21, v13, v20
	v_cvt_pk_bf16_f32 v28, v60, v61
	v_cvt_pk_bf16_f32 v29, v44, v45
	v_cvt_pk_bf16_f32 v30, v62, v63
	v_cvt_pk_bf16_f32 v31, v46, v47
	s_waitcnt lgkmcnt(0)
	v_add_f32_e32 v20, v20, v21
	ds_bpermute_b32 v21, v14, v20
	v_cvt_pk_bf16_f32 v32, v64, v65
	v_cvt_pk_bf16_f32 v33, v48, v49
	v_cvt_pk_bf16_f32 v35, v50, v51
	v_cvt_pk_bf16_f32 v34, v66, v67
	s_waitcnt lgkmcnt(0)
	v_add_f32_e32 v20, v20, v21
	ds_bpermute_b32 v21, v15, v20
	s_waitcnt lgkmcnt(0)
	v_add_f32_e32 v20, v20, v21
	ds_bpermute_b32 v21, v16, v20
	s_waitcnt lgkmcnt(0)
	v_add_f32_e32 v20, v20, v21
	ds_bpermute_b32 v21, v17, v20
	s_waitcnt lgkmcnt(0)
	v_add_f32_e32 v20, v20, v21
	v_fmamk_f32 v20, v20, 0x3a000000, v18
	v_mul_f32_e32 v21, 0x4b800000, v20
	v_cmp_gt_f32_e32 vcc, s41, v20
	s_nop 1
	v_cndmask_b32_e32 v20, v20, v21, vcc
	v_rsq_f32_e32 v20, v20
	s_nop 0
	v_mul_f32_e32 v21, 0x45800000, v20
	v_cndmask_b32_e32 v20, v20, v21, vcc
	v_pk_mul_f32 v[10:11], v[10:11], v[20:21] op_sel_hi:[1,0]
	v_pk_mul_f32 v[22:23], v[36:37], v[20:21] op_sel_hi:[1,0]
	v_pk_mul_f32 v[36:37], v[54:55], v[20:21] op_sel_hi:[1,0]
	v_pk_mul_f32 v[38:39], v[38:39], v[20:21] op_sel_hi:[1,0]
	v_pk_mul_f32 v[54:55], v[56:57], v[20:21] op_sel_hi:[1,0]
	v_pk_mul_f32 v[40:41], v[40:41], v[20:21] op_sel_hi:[1,0]
	v_pk_mul_f32 v[56:57], v[58:59], v[20:21] op_sel_hi:[1,0]
	v_pk_mul_f32 v[42:43], v[42:43], v[20:21] op_sel_hi:[1,0]
	v_pk_mul_f32 v[58:59], v[60:61], v[20:21] op_sel_hi:[1,0]
	v_pk_mul_f32 v[44:45], v[44:45], v[20:21] op_sel_hi:[1,0]
	v_pk_mul_f32 v[60:61], v[62:63], v[20:21] op_sel_hi:[1,0]
	v_pk_mul_f32 v[46:47], v[46:47], v[20:21] op_sel_hi:[1,0]
	v_pk_mul_f32 v[62:63], v[64:65], v[20:21] op_sel_hi:[1,0]
	v_pk_mul_f32 v[48:49], v[48:49], v[20:21] op_sel_hi:[1,0]
	v_pk_mul_f32 v[64:65], v[66:67], v[20:21] op_sel_hi:[1,0]
	v_pk_mul_f32 v[50:51], v[50:51], v[20:21] op_sel_hi:[1,0]
	v_cvt_pk_bf16_f32 v20, v10, v11
	v_cvt_pk_bf16_f32 v21, v22, v23
	v_cvt_pk_bf16_f32 v22, v36, v37
	v_cvt_pk_bf16_f32 v23, v38, v39
	v_cvt_pk_bf16_f32 v36, v54, v55
	v_cvt_pk_bf16_f32 v37, v40, v41
	v_cvt_pk_bf16_f32 v38, v56, v57
	v_cvt_pk_bf16_f32 v39, v42, v43
	v_cvt_pk_bf16_f32 v40, v58, v59
	v_cvt_pk_bf16_f32 v41, v44, v45
	v_cvt_pk_bf16_f32 v42, v60, v61
	v_cvt_pk_bf16_f32 v43, v46, v47
	v_cvt_pk_bf16_f32 v44, v62, v63
	v_cvt_pk_bf16_f32 v45, v48, v49
	v_cvt_pk_bf16_f32 v46, v64, v65
	v_cvt_pk_bf16_f32 v47, v50, v51
	global_store_dwordx4 v[52:53], v[20:23], off
	global_store_dwordx4 v[8:9], v[24:27], off offset:1024
	global_store_dwordx4 v[52:53], v[36:39], off offset:1024
	global_store_dwordx4 v[8:9], v[28:31], off offset:2048
	global_store_dwordx4 v[52:53], v[40:43], off offset:2048
	global_store_dwordx4 v[8:9], v[32:35], off offset:3072
	global_store_dwordx4 v[52:53], v[44:47], off offset:3072
	s_andn2_b64 exec, exec, s[14:15]
	s_cbranch_execnz .LBB0_1075
